# v32 + differential QK: the S0 row max first, then the last three S1 MFMAs back to back (no VALU inside the S1 chain)
# speedup vs baseline: 1.0083x; 1.0040x over previous
; #define A2_SETKC(SOFF) _Pragma("unroll") for (int _i = 0; _i < NKB; ++_i) kc[_i] = kbase[_i] + (unsigned)(SOFF)
; #define A2_SETVC(SOFF) _Pragma("unroll") for (int _i = 0; _i < 4; ++_i) vc[_i] = vbase[_i] + (unsigned)(SOFF)
; template <int TYPE>
; __device__ __forceinline__ void attn_mfma_unit2(const AttnCtx& A, unsigned char* ws, LAS unsigned char* lds, int tid, const AUnit& u) {
;     ...
;         for (int ti = 0; ti < nt; ++ti) {
;             if (ti + 1 < nt) A2_DMA(ti + 1, snxt);
;             if (actP) { A2_SETVC(sprv); A2_FSM_PV(sA0, sA1, 0); }
;             actP = A2_ACTIVE(ti);
;             if (actP) { A2_SETKC(scur); A2_QK(sA0, sA1, ti, 0); A2_PSM(sA0, sA1); }
.LBB0_2781:
	s_add_i32 s46, s15, 1
	s_cmp_lt_u32 s15, 3
	s_cselect_b32 s48, s46, s15
	s_cselect_b32 s49, s38, s39
	s_lshl_b32 s48, s48, 6
	s_add_i32 s48, s48, s49
	s_ashr_i32 s49, s48, 31
	s_lshl_b64 s[50:51], s[48:49], 1
	s_add_u32 s50, s12, s50
	v_mad_i64_i32 v[2:3], s[48:49], s48, v242, v[132:133]
	s_addc_u32 s51, s13, s51
	s_add_i32 s48, s14, s6
	s_mov_b32 m0, s48
	s_nop 0
	global_load_lds_dwordx4 v[2:3], off
	s_add_i32 m0, s48, 0x2000
	v_lshl_add_u64 v[2:3], v[128:129], 1, s[50:51]
	global_load_lds_dwordx4 v[2:3], off
	v_lshl_add_u64 v[2:3], v[130:131], 1, s[50:51]
	s_add_i32 m0, s48, 0x4000
	s_mov_b32 s48, s7
	global_load_lds_dwordx4 v[2:3], off
	v_add_u32_e32 v0, s48, v137
	ds_read_b128 v[2:5], v0 offset:8192
	ds_read_b128 v[6:9], v0 offset:12288
	ds_read_b128 v[10:13], v0 offset:16384
	ds_read_b128 v[140:143], v0 offset:20480
	s_mov_b32 s7, s47
	v_exp_f32_e32 v14, v96
	v_exp_f32_e32 v144, v97
	v_exp_f32_e32 v98, v98
	v_exp_f32_e32 v146, v99
	v_exp_f32_e32 v15, v100
	v_exp_f32_e32 v145, v101
	v_exp_f32_e32 v99, v102
	v_exp_f32_e32 v147, v103
	v_add_u32_e32 v0, s48, v136
	v_pk_add_f32 v[96:97], v[14:15], v[144:145]
	v_pk_add_f32 v[100:101], v[98:99], v[146:147]
	s_nop 0
	v_pk_add_f32 v[96:97], v[96:97], v[100:101]
	v_cvt_pk_bf16_f32 v99, v99, v147
	v_pk_add_f32 v[156:157], v[96:97], v[96:97] op_sel_hi:[0,1]
	v_cvt_pk_bf16_f32 v96, v14, v144
	v_cvt_pk_bf16_f32 v97, v98, v146
	v_cvt_pk_bf16_f32 v98, v15, v145
	ds_read_b128 v[100:103], v0 offset:8192
	ds_read_b128 v[144:147], v0 offset:12288
	ds_read_b128 v[148:151], v0 offset:16384
	ds_read_b128 v[152:155], v0 offset:20480
	s_waitcnt lgkmcnt(0)
	v_mfma_f32_32x32x16_bf16 v[64:79], v[2:5], v[96:99], v[64:79]
	v_mfma_f32_32x32x16_bf16 v[48:63], v[6:9], v[96:99], v[48:63]
	v_mfma_f32_32x32x16_bf16 v[32:47], v[10:13], v[96:99], v[32:47]
	v_mfma_f32_32x32x16_bf16 v[16:31], v[140:143], v[96:99], v[16:31]
	v_exp_f32_e32 v2, v104
	v_exp_f32_e32 v4, v105
	v_exp_f32_e32 v3, v106
	v_exp_f32_e32 v5, v107
	v_exp_f32_e32 v6, v108
	v_exp_f32_e32 v8, v109
	v_exp_f32_e32 v7, v110
	v_exp_f32_e32 v9, v111
	v_pk_add_f32 v[10:11], v[2:3], v[4:5]
	v_add_u32_e32 v0, s48, v135
	v_pk_add_f32 v[14:15], v[10:11], v[10:11] op_sel_hi:[0,1]
	v_pk_add_f32 v[10:11], v[6:7], v[8:9]
	v_cvt_pk_bf16_f32 v2, v2, v4
	v_pk_add_f32 v[140:141], v[10:11], v[10:11] op_sel_hi:[0,1]
	v_cvt_pk_bf16_f32 v3, v3, v5
	v_cvt_pk_bf16_f32 v4, v6, v8
	v_cvt_pk_bf16_f32 v5, v7, v9
	ds_read_b128 v[6:9], v0 offset:8192
	ds_read_b128 v[10:13], v0 offset:12288
	ds_read_b128 v[96:99], v0 offset:16384
	ds_read_b128 v[104:107], v0 offset:20480
	v_mfma_f32_32x32x16_bf16 v[64:79], v[100:103], v[2:5], v[64:79]
	v_mfma_f32_32x32x16_bf16 v[48:63], v[144:147], v[2:5], v[48:63]
	v_mfma_f32_32x32x16_bf16 v[32:47], v[148:151], v[2:5], v[32:47]
	v_mfma_f32_32x32x16_bf16 v[16:31], v[152:155], v[2:5], v[16:31]
	v_exp_f32_e32 v0, v80
	v_exp_f32_e32 v2, v81
	v_exp_f32_e32 v3, v82
	v_exp_f32_e32 v4, v83
	v_exp_f32_e32 v5, v84
	v_exp_f32_e32 v14, v85
	v_exp_f32_e32 v80, v86
	v_exp_f32_e32 v81, v87
	v_add_f32_e32 v143, v0, v2
	v_cvt_pk_bf16_f32 v2, v0, v2
	v_add_u32_e32 v0, s48, v134
	v_add_f32_e32 v145, v3, v4
	v_add_f32_e32 v147, v5, v14
	v_add_f32_e32 v149, v80, v81
	v_cvt_pk_bf16_f32 v3, v3, v4
	v_cvt_pk_bf16_f32 v4, v5, v14
	v_cvt_pk_bf16_f32 v5, v80, v81
	ds_read_b128 v[80:83], v0 offset:8192
	ds_read_b128 v[84:87], v0 offset:12288
	ds_read_b128 v[100:103], v0 offset:16384
	ds_read_b128 v[108:111], v0 offset:20480
	s_waitcnt lgkmcnt(0)
	v_mfma_f32_32x32x16_bf16 v[64:79], v[6:9], v[2:5], v[64:79]
	v_mfma_f32_32x32x16_bf16 v[48:63], v[10:13], v[2:5], v[48:63]
	v_mfma_f32_32x32x16_bf16 v[32:47], v[96:99], v[2:5], v[32:47]
	v_mfma_f32_32x32x16_bf16 v[16:31], v[104:107], v[2:5], v[16:31]
	v_exp_f32_e32 v142, v88
	v_exp_f32_e32 v144, v89
	v_exp_f32_e32 v146, v90
	v_exp_f32_e32 v148, v91
	v_exp_f32_e32 v14, v92
	v_exp_f32_e32 v140, v93
	v_exp_f32_e32 v156, v94
	v_exp_f32_e32 v0, v95
	v_cvt_pk_bf16_f32 v2, v142, v144
	v_cvt_pk_bf16_f32 v3, v146, v148
	v_cvt_pk_bf16_f32 v4, v14, v140
	v_cvt_pk_bf16_f32 v5, v156, v0
	s_nop 1
	v_mfma_f32_32x32x16_bf16 v[64:79], v[80:83], v[2:5], v[64:79]
	v_add_f32_e64 v6, v142, v144
	v_add_f32_e64 v7, v143, v145
	v_add_f32_e64 v8, v146, v148
	v_add_f32_e64 v9, v147, v149
	v_add_f32_e64 v10, v156, v0
	v_add_f32_e64 v11, v157, v1
	v_pk_add_f32 v[6:7], v[6:7], v[8:9]
	v_pk_add_f32 v[8:9], v[14:15], v[140:141]
	s_nop 0
	v_pk_add_f32 v[8:9], v[8:9], v[10:11]
	v_mfma_f32_32x32x16_bf16 v[48:63], v[84:87], v[2:5], v[48:63]
	v_add_f32_e64 v6, v6, v8
	v_add_f32_e64 v7, v7, v9
	v_pk_add_f32 v[6:7], v[6:7], v[6:7] op_sel:[0,1] op_sel_hi:[1,0]
	v_mfma_f32_32x32x16_bf16 v[32:47], v[100:103], v[2:5], v[32:47]
	v_mfma_f32_32x32x16_bf16 v[16:31], v[108:111], v[2:5], v[16:31]
	v_mov_b32_e32 v0, v6
	s_nop 1
	v_permlane32_swap_b32_e32 v6, v0
	v_add_f32_e32 v0, v6, v0
	v_add_f32_e32 v139, v139, v0
	v_add_u32_e32 v0, s7, v137
	ds_read_b128 v[2:5], v0
	ds_read_b128 v[6:9], v0 offset:4096
	v_add_u32_e32 v0, s7, v136
	ds_read_b128 v[10:13], v0
	ds_read_b128 v[140:143], v0 offset:4096
	v_add_u32_e32 v0, s7, v135
	v_add_u32_e32 v14, s7, v134
	ds_read_b128 v[144:147], v0
	ds_read_b128 v[148:151], v0 offset:4096
	ds_read_b128 v[152:155], v14
	ds_read_b128 v[156:159], v14 offset:4096
	v_xor_b32_e32 v80, 0x80000000, v138
	v_mov_b32_e32 v81, v80
	v_mov_b32_e32 v82, v80
	v_mov_b32_e32 v83, v80
	v_mov_b32_e32 v84, v80
	v_mov_b32_e32 v85, v80
	v_mov_b32_e32 v86, v80
	v_mov_b32_e32 v87, v80
	v_mov_b32_e32 v88, v80
	v_mov_b32_e32 v89, v80
	v_mov_b32_e32 v90, v80
	v_mov_b32_e32 v91, v80
	v_mov_b32_e32 v92, v80
	v_mov_b32_e32 v93, v80
	v_mov_b32_e32 v94, v80
	v_mov_b32_e32 v95, v80
	s_waitcnt lgkmcnt(0)
	s_nop 0
	v_mfma_f32_32x32x16_bf16 v[96:111], v[2:5], v[124:127], v[80:95]
	v_mfma_f32_32x32x16_bf16 v[96:111], v[10:13], v[120:123], v[96:111]
	v_mfma_f32_32x32x16_bf16 v[96:111], v[144:147], v[116:119], v[96:111]
	v_mfma_f32_32x32x16_bf16 v[96:111], v[152:155], v[112:115], v[96:111]
	v_mfma_f32_32x32x16_bf16 v[80:95], v[6:9], v[124:127], v[80:95]
	s_nop 10
	v_max_f32_e32 v0, v97, v97
	v_max_f32_e32 v2, v96, v96
	v_max_f32_e32 v0, v2, v0
	v_max3_f32 v0, v0, v98, v99
	v_max3_f32 v0, v0, v100, v101
	v_max3_f32 v0, v0, v102, v103
	v_max3_f32 v0, v0, v104, v105
	v_max3_f32 v0, v0, v106, v107
	v_max3_f32 v0, v0, v108, v109
	v_max3_f32 v0, v0, v110, v111
	s_mov_b32 s47, 0x41000000
	v_mfma_f32_32x32x16_bf16 v[80:95], v[140:143], v[120:123], v[80:95]
	v_mfma_f32_32x32x16_bf16 v[80:95], v[148:151], v[116:119], v[80:95]
	v_mfma_f32_32x32x16_bf16 v[80:95], v[156:159], v[112:115], v[80:95]
	s_nop 11
	v_max3_f32 v0, v0, v80, v81
	v_max3_f32 v0, v0, v82, v83
	v_max3_f32 v0, v0, v84, v85
	v_max3_f32 v0, v0, v86, v87
	v_max3_f32 v0, v0, v88, v89
	v_max3_f32 v0, v0, v90, v91
	v_max3_f32 v0, v0, v92, v93
	v_max3_f32 v0, v0, v94, v95
	v_mov_b32_e32 v2, v0
	s_nop 1
	v_permlane32_swap_b32_e32 v0, v2
	v_max_f32_e32 v2, v2, v2
	v_max_f32_e32 v0, v0, v0
	v_max_f32_e32 v0, v0, v2
	v_cmp_ge_f32_e32 vcc, s47, v0
	s_cmp_eq_u64 vcc, exec
	s_cbranch_scc1 .LBB0_2783
	v_max_f32_e32 v0, v0, v0
	v_max_f32_e32 v2, 0, v0
	v_exp_f32_e64 v0, -v2
	v_add_f32_e32 v138, v138, v2
	v_sub_f32_e32 v111, v111, v2
	v_sub_f32_e32 v110, v110, v2
	v_pk_mul_f32 v[78:79], v[78:79], v[0:1] op_sel_hi:[1,0]
	v_pk_mul_f32 v[76:77], v[76:77], v[0:1] op_sel_hi:[1,0]
	v_pk_mul_f32 v[74:75], v[74:75], v[0:1] op_sel_hi:[1,0]
	v_pk_mul_f32 v[72:73], v[72:73], v[0:1] op_sel_hi:[1,0]
	v_pk_mul_f32 v[70:71], v[70:71], v[0:1] op_sel_hi:[1,0]
	v_pk_mul_f32 v[68:69], v[68:69], v[0:1] op_sel_hi:[1,0]
	v_pk_mul_f32 v[66:67], v[66:67], v[0:1] op_sel_hi:[1,0]
	v_pk_mul_f32 v[64:65], v[64:65], v[0:1] op_sel_hi:[1,0]
	v_pk_mul_f32 v[62:63], v[62:63], v[0:1] op_sel_hi:[1,0]
	v_pk_mul_f32 v[60:61], v[60:61], v[0:1] op_sel_hi:[1,0]
	v_pk_mul_f32 v[58:59], v[58:59], v[0:1] op_sel_hi:[1,0]
	v_pk_mul_f32 v[56:57], v[56:57], v[0:1] op_sel_hi:[1,0]
	v_pk_mul_f32 v[54:55], v[54:55], v[0:1] op_sel_hi:[1,0]
	v_pk_mul_f32 v[52:53], v[52:53], v[0:1] op_sel_hi:[1,0]
	v_pk_mul_f32 v[50:51], v[50:51], v[0:1] op_sel_hi:[1,0]
	v_pk_mul_f32 v[48:49], v[48:49], v[0:1] op_sel_hi:[1,0]
	v_pk_mul_f32 v[46:47], v[46:47], v[0:1] op_sel_hi:[1,0]
	v_pk_mul_f32 v[44:45], v[44:45], v[0:1] op_sel_hi:[1,0]
	v_pk_mul_f32 v[42:43], v[42:43], v[0:1] op_sel_hi:[1,0]
	v_pk_mul_f32 v[40:41], v[40:41], v[0:1] op_sel_hi:[1,0]
	v_pk_mul_f32 v[38:39], v[38:39], v[0:1] op_sel_hi:[1,0]
	v_pk_mul_f32 v[36:37], v[36:37], v[0:1] op_sel_hi:[1,0]
	v_pk_mul_f32 v[34:35], v[34:35], v[0:1] op_sel_hi:[1,0]
	v_pk_mul_f32 v[32:33], v[32:33], v[0:1] op_sel_hi:[1,0]
	v_pk_mul_f32 v[30:31], v[30:31], v[0:1] op_sel_hi:[1,0]
	v_pk_mul_f32 v[28:29], v[28:29], v[0:1] op_sel_hi:[1,0]
	v_pk_mul_f32 v[26:27], v[26:27], v[0:1] op_sel_hi:[1,0]
	v_pk_mul_f32 v[24:25], v[24:25], v[0:1] op_sel_hi:[1,0]
	v_pk_mul_f32 v[22:23], v[22:23], v[0:1] op_sel_hi:[1,0]
	v_pk_mul_f32 v[20:21], v[20:21], v[0:1] op_sel_hi:[1,0]
	v_pk_mul_f32 v[18:19], v[18:19], v[0:1] op_sel_hi:[1,0]
	v_pk_mul_f32 v[16:17], v[16:17], v[0:1] op_sel_hi:[1,0]
	v_sub_f32_e32 v109, v109, v2
	v_sub_f32_e32 v108, v108, v2
	v_sub_f32_e32 v107, v107, v2
	v_sub_f32_e32 v106, v106, v2
	v_sub_f32_e32 v105, v105, v2
	v_sub_f32_e32 v104, v104, v2
	v_sub_f32_e32 v103, v103, v2
	v_sub_f32_e32 v102, v102, v2
	v_sub_f32_e32 v101, v101, v2
	v_sub_f32_e32 v100, v100, v2
	v_sub_f32_e32 v99, v99, v2
	v_sub_f32_e32 v98, v98, v2
	v_sub_f32_e32 v97, v97, v2
	v_sub_f32_e32 v96, v96, v2
	v_sub_f32_e32 v95, v95, v2
	v_sub_f32_e32 v94, v94, v2
	v_sub_f32_e32 v93, v93, v2
	v_sub_f32_e32 v92, v92, v2
	v_sub_f32_e32 v91, v91, v2
	v_sub_f32_e32 v90, v90, v2
	v_sub_f32_e32 v89, v89, v2
	v_sub_f32_e32 v88, v88, v2
	v_sub_f32_e32 v87, v87, v2
	v_sub_f32_e32 v86, v86, v2
	v_sub_f32_e32 v85, v85, v2
	v_sub_f32_e32 v84, v84, v2
	v_sub_f32_e32 v83, v83, v2
	v_sub_f32_e32 v82, v82, v2
	v_sub_f32_e32 v81, v81, v2
	v_sub_f32_e32 v80, v80, v2
	v_mul_f32_e32 v139, v139, v0
